# proj GEMM: rotate column tile by 4 per outer iteration to balance epilogue kinds across workgroups
# speedup vs baseline: 1.0500x; 1.0500x over previous
.LBB0_119:
	s_ashr_i32 s8, s54, 5
	s_lshr_b32 s98, s54, 9
	s_lshl2_add_u32 s98, s98, s54
	s_and_b32 s11, s98, 31
	s_lshl_b32 s55, s8, 7
	s_lshl_b32 s10, s11, 7
	v_add_u32_e32 v0, s55, v134
	s_movk_i32 s0, 0x440
	v_mul_lo_u32 v8, v0, s0
	v_add_u32_e32 v0, s10, v134
	v_add_u32_e32 v9, 0x4400, v8
	v_mul_u32_u24_e32 v0, 0x440, v0
	v_or_b32_e32 v132, v8, v135
	v_mov_b32_e32 v133, v129
	v_readfirstlane_b32 s0, v149
	v_or_b32_e32 v130, v0, v135
	s_waitcnt vmcnt(0)
	v_lshl_add_u64 v[0:1], v[132:133], 1, s[90:91]
	s_mov_b32 m0, s0
	v_or_b32_e32 v128, v9, v135
	v_readfirstlane_b32 s0, v190
	v_readlane_b32 s36, v255, 45
	global_load_lds_dwordx4 v[0:1], off
	v_lshl_add_u64 v[2:3], v[128:129], 1, s[90:91]
	s_mov_b32 m0, s0
	v_mov_b32_e32 v131, v129
	v_readlane_b32 s48, v255, 57
	v_readlane_b32 s49, v255, 58
	v_readfirstlane_b32 s0, v191
	global_load_lds_dwordx4 v[2:3], off
	v_lshl_add_u64 v[4:5], v[130:131], 1, s[48:49]
	s_mov_b32 m0, s0
	s_mov_b64 s[0:1], 0x8800
	v_lshl_add_u64 v[6:7], v[4:5], 0, s[0:1]
	v_readfirstlane_b32 s0, v192
	global_load_lds_dwordx4 v[4:5], off
	s_mov_b32 m0, s0
	v_readfirstlane_b32 s0, v193
	global_load_lds_dwordx4 v[6:7], off
	v_lshl_add_u64 v[0:1], v[0:1], 0, 64
	s_mov_b32 m0, s0
	v_readfirstlane_b32 s0, v194
	global_load_lds_dwordx4 v[0:1], off
	v_lshl_add_u64 v[0:1], v[2:3], 0, 64
	s_mov_b32 m0, s0
	v_readfirstlane_b32 s0, v195
	global_load_lds_dwordx4 v[0:1], off
	v_lshl_add_u64 v[0:1], v[4:5], 0, 64
	s_mov_b32 m0, s0
	s_mov_b64 s[0:1], 0x8840
	global_load_lds_dwordx4 v[0:1], off
	v_lshl_add_u64 v[0:1], v[4:5], 0, s[0:1]
	v_readfirstlane_b32 s0, v196
	s_mov_b32 m0, s0
	v_add_u32_e32 v128, v8, v140
	v_readfirstlane_b32 s0, v197
	global_load_lds_dwordx4 v[0:1], off
	v_lshl_add_u64 v[0:1], v[128:129], 1, s[90:91]
	s_mov_b32 m0, s0
	v_add_u32_e32 v128, v9, v140
	v_readfirstlane_b32 s0, v198
	global_load_lds_dwordx4 v[0:1], off
	v_lshl_add_u64 v[0:1], v[128:129], 1, s[90:91]
	s_mov_b32 m0, s0
	s_mov_b64 s[0:1], 0x80
	global_load_lds_dwordx4 v[0:1], off
	v_lshl_add_u64 v[0:1], v[4:5], 0, s[0:1]
	v_readfirstlane_b32 s0, v199
	s_mov_b32 m0, s0
	s_mov_b64 s[0:1], 0x8880
	global_load_lds_dwordx4 v[0:1], off
	v_lshl_add_u64 v[0:1], v[4:5], 0, s[0:1]
	v_readfirstlane_b32 s0, v200
	s_mov_b32 m0, s0
	v_add_u32_e32 v128, v8, v141
	global_load_lds_dwordx4 v[0:1], off
	v_readfirstlane_b32 s0, v201
	s_waitcnt vmcnt(8)
	v_lshl_add_u64 v[0:1], v[128:129], 1, s[90:91]
	s_mov_b32 m0, s0
	v_add_u32_e32 v128, v9, v141
	v_readfirstlane_b32 s0, v202
	s_waitcnt lgkmcnt(0)
	s_barrier
	global_load_lds_dwordx4 v[0:1], off
	v_lshl_add_u64 v[0:1], v[128:129], 1, s[90:91]
	s_mov_b32 m0, s0
	s_mov_b64 s[0:1], 0xc0
	global_load_lds_dwordx4 v[0:1], off
	v_lshl_add_u64 v[0:1], v[4:5], 0, s[0:1]
	v_readfirstlane_b32 s0, v203
	s_mov_b32 m0, s0
	s_mov_b64 s[0:1], 0x88c0
	global_load_lds_dwordx4 v[0:1], off
	v_lshl_add_u64 v[0:1], v[4:5], 0, s[0:1]
	v_readfirstlane_b32 s0, v204
	s_mov_b32 m0, s0
	s_mov_b32 s0, 0
	global_load_lds_dwordx4 v[0:1], off
	s_mov_b32 s1, 0
	v_mov_b32_e32 v0, v129
	v_mov_b32_e32 v1, v129
	v_mov_b32_e32 v2, v129
	v_mov_b32_e32 v3, v129
	v_mov_b32_e32 v4, v129
	v_mov_b32_e32 v5, v129
	v_mov_b32_e32 v6, v129
	v_mov_b32_e32 v7, v129
	v_mov_b32_e32 v8, v129
	v_mov_b32_e32 v9, v129
	v_mov_b32_e32 v10, v129
	v_mov_b32_e32 v11, v129
	v_mov_b32_e32 v12, v129
	v_mov_b32_e32 v13, v129
	v_mov_b32_e32 v14, v129
	v_mov_b32_e32 v15, v129
	v_mov_b32_e32 v16, v129
	v_mov_b32_e32 v17, v129
	v_mov_b32_e32 v18, v129
	v_mov_b32_e32 v19, v129
	v_mov_b32_e32 v20, v129
	v_mov_b32_e32 v21, v129
	v_mov_b32_e32 v22, v129
	v_mov_b32_e32 v23, v129
	v_mov_b32_e32 v24, v129
	v_mov_b32_e32 v25, v129
	v_mov_b32_e32 v26, v129
	v_mov_b32_e32 v27, v129
	v_mov_b32_e32 v28, v129
	v_mov_b32_e32 v29, v129
	v_mov_b32_e32 v30, v129
	v_mov_b32_e32 v31, v129
	v_mov_b32_e32 v32, v129
	v_mov_b32_e32 v33, v129
	v_mov_b32_e32 v34, v129
	v_mov_b32_e32 v35, v129
	v_mov_b32_e32 v36, v129
	v_mov_b32_e32 v37, v129
	v_mov_b32_e32 v38, v129
	v_mov_b32_e32 v39, v129
	v_mov_b32_e32 v40, v129
	v_mov_b32_e32 v41, v129
	v_mov_b32_e32 v42, v129
	v_mov_b32_e32 v43, v129
	v_mov_b32_e32 v44, v129
	v_mov_b32_e32 v45, v129
	v_mov_b32_e32 v46, v129
	v_mov_b32_e32 v47, v129
	v_mov_b32_e32 v48, v129
	v_mov_b32_e32 v49, v129
	v_mov_b32_e32 v50, v129
	v_mov_b32_e32 v51, v129
	v_mov_b32_e32 v52, v129
	v_mov_b32_e32 v53, v129
	v_mov_b32_e32 v54, v129
	v_mov_b32_e32 v55, v129
	v_mov_b32_e32 v56, v129
	v_mov_b32_e32 v57, v129
	v_mov_b32_e32 v58, v129
	v_mov_b32_e32 v59, v129
	v_mov_b32_e32 v60, v129
	v_mov_b32_e32 v61, v129
	v_mov_b32_e32 v62, v129
	v_mov_b32_e32 v63, v129
	v_readlane_b32 s37, v255, 46
	v_readlane_b32 s38, v255, 47
	v_readlane_b32 s39, v255, 48
	v_readlane_b32 s40, v255, 49
	v_readlane_b32 s41, v255, 50
	v_readlane_b32 s42, v255, 51
	v_readlane_b32 s43, v255, 52
	v_readlane_b32 s44, v255, 53
	v_readlane_b32 s45, v255, 54
	v_readlane_b32 s46, v255, 55
	v_readlane_b32 s47, v255, 56
	v_readlane_b32 s50, v255, 59
	v_readlane_b32 s51, v255, 60
	ds_read_b128 v[64:67], v136 offset:0
	ds_read_b128 v[68:71], v136 offset:0x800
	ds_read_b128 v[76:79], v138 offset:0
	ds_read_b128 v[80:83], v138 offset:0x800
	ds_read_b128 v[84:87], v137 offset:0
	ds_read_b128 v[72:75], v137 offset:0x800
	ds_read_b128 v[92:95], v139 offset:0
	ds_read_b128 v[88:91], v139 offset:0x800
	s_branch .LBB0_122

	.amdhsa_kernel _Z4mega6Params
		.amdhsa_group_segment_fixed_size 65536
		.amdhsa_private_segment_fixed_size 0
		.amdhsa_kernarg_size 752
		.amdhsa_user_sgpr_count 2
		.amdhsa_user_sgpr_dispatch_ptr 0
		.amdhsa_user_sgpr_queue_ptr 0
		.amdhsa_user_sgpr_kernarg_segment_ptr 1
		.amdhsa_user_sgpr_dispatch_id 0
		.amdhsa_user_sgpr_kernarg_preload_length 0
		.amdhsa_user_sgpr_kernarg_preload_offset 0
		.amdhsa_user_sgpr_private_segment_size 0
		.amdhsa_uses_dynamic_stack 0
		.amdhsa_enable_private_segment 0
		.amdhsa_system_sgpr_workgroup_id_x 1
		.amdhsa_system_sgpr_workgroup_id_y 0
		.amdhsa_system_sgpr_workgroup_id_z 0
		.amdhsa_system_sgpr_workgroup_info 0
		.amdhsa_system_vgpr_workitem_id 2
		.amdhsa_next_free_vgpr 256
		.amdhsa_next_free_sgpr 102
		.amdhsa_accum_offset 256
		.amdhsa_reserve_vcc 1
		.amdhsa_float_round_mode_32 0
		.amdhsa_float_round_mode_16_64 0
		.amdhsa_float_denorm_mode_32 3
		.amdhsa_float_denorm_mode_16_64 3
		.amdhsa_dx10_clamp 1
		.amdhsa_ieee_mode 1
		.amdhsa_fp16_overflow 0
		.amdhsa_tg_split 0
		.amdhsa_exception_fp_ieee_invalid_op 0
		.amdhsa_exception_fp_denorm_src 0
		.amdhsa_exception_fp_ieee_div_zero 0
		.amdhsa_exception_fp_ieee_overflow 0
		.amdhsa_exception_fp_ieee_underflow 0
		.amdhsa_exception_fp_ieee_inexact 0
		.amdhsa_exception_int_div_zero 0
	.end_amdhsa_kernel

amdhsa.kernels:
  - .agpr_count:     0
    .args:
      - .offset:         0
        .size:           496
        .value_kind:     by_value
      - .offset:         496
        .size:           4
        .value_kind:     hidden_block_count_x
      - .offset:         500
        .size:           4
        .value_kind:     hidden_block_count_y
      - .offset:         504
        .size:           4
        .value_kind:     hidden_block_count_z
      - .offset:         508
        .size:           2
        .value_kind:     hidden_group_size_x
      - .offset:         510
        .size:           2
        .value_kind:     hidden_group_size_y
      - .offset:         512
        .size:           2
        .value_kind:     hidden_group_size_z
      - .offset:         514
        .size:           2
        .value_kind:     hidden_remainder_x
      - .offset:         516
        .size:           2
        .value_kind:     hidden_remainder_y
      - .offset:         518
        .size:           2
        .value_kind:     hidden_remainder_z
      - .offset:         536
        .size:           8
        .value_kind:     hidden_global_offset_x
      - .offset:         544
        .size:           8
        .value_kind:     hidden_global_offset_y
      - .offset:         552
        .size:           8
        .value_kind:     hidden_global_offset_z
      - .offset:         560
        .size:           2
        .value_kind:     hidden_grid_dims
      - .offset:         584
        .size:           8
        .value_kind:     hidden_multigrid_sync_arg
    .group_segment_fixed_size: 65536
    .kernarg_segment_align: 8
    .kernarg_segment_size: 752
    .language:       OpenCL C
    .language_version:
      - 2
      - 0
    .max_flat_workgroup_size: 256
    .name:           _Z4mega6Params
    .private_segment_fixed_size: 0
    .sgpr_count:     108
    .sgpr_spill_count: 141
    .symbol:         _Z4mega6Params.kd
    .uniform_work_group_size: 1
    .uses_dynamic_stack: false
    .vgpr_count:     256
    .vgpr_spill_count: 0
    .wavefront_size: 64
